# V tile stored in natural key order so P needs no permlane swaps before the PV MFMAs (16 fewer cross-lane ops per tile iteration)
# baseline (speedup 1.0000x reference)
; __device__ __forceinline__ int v_st(int k, int c) { const int kk = (k & ~0xC) | ((k & 4) << 1) | ((k & 8) >> 1); return ((kk >> 3) * 4 + (c >> 5)) * 512 + ((kk & 7) * 32 + (c & 31)) * 2; }
; __device__ __forceinline__ int v_rd_base(int lane) { return ((lane & 3) << 3) | (((lane >> 2) & 3) << 6) | (((lane >> 4) & 1) << 5) | (((lane >> 5) & 1) << 8); }
; __device__ __forceinline__ void attn_body(const bf16_t* __restrict__ Qb, const bf16_t* __restrict__ KVh, const bf16_t* __restrict__ KR, const float* __restrict__ ropeq,
;                                           bf16_t* __restrict__ Ob, int seq, char* lds, const int tid) {
;     ...
;     const int sr = tid >> 4, c16 = tid & 15;
;     const bool isK = c16 < 8;
;     const int kst0 = KSWZ(sr, c16 * 16), kst1 = KSWZ(32 + sr, c16 * 16), vst0 = v_st(sr, (c16 & 7) * 8), vst1 = v_st(32 + sr, (c16 & 7) * 8);
;     const int rkey = (tid & 255) >> 2, rch = tid & 3; const int rst = KSWZ(rkey, 128 + rch * 16); const bool rwr = tid < 256;
;     const int vb0 = (int)(uintptr_t)V_lds + v_rd_base(lane);
.LBB0_39:
	s_andn2_b64 vcc, exec, s[0:1]
	s_cbranch_vccnz .LBB0_79
	s_cmpk_gt_i32 s89, 0x3ff
	s_cbranch_scc1 .LBB0_78
	v_and_b32_e32 v2, 0x3fffffc0, v140
	s_add_i32 s0, 0, 0x18000
	v_lshl_add_u32 v139, v2, 2, s0
	v_ashrrev_i32_e32 v3, 1, v140
	s_movk_i32 s0, 0xffe0
	v_bfi_b32 v4, s0, v3, v140
	s_movk_i32 s0, 0xc00
	v_mad_i64_i32 v[130:131], s[0:1], v4, s0, 0
	v_ashrrev_i32_e32 v5, 31, v4
	v_readlane_b32 s0, v253, 43
	v_lshlrev_b64 v[4:5], 7, v[4:5]
	v_readlane_b32 s1, v253, 44
	v_and_b32_e32 v64, 32, v211
	v_and_b32_e32 v2, 0xffffffe0, v3
	v_lshl_add_u64 v[4:5], s[0:1], 0, v[4:5]
	v_lshl_add_u64 v[132:133], v[4:5], 0, v[64:65]
	v_ashrrev_i32_e32 v4, 4, v140
	v_and_b32_e32 v3, 15, v140
	v_lshlrev_b32_e32 v5, 8, v4
	v_lshlrev_b32_e32 v7, 4, v3
	v_and_b32_e32 v9, 0x70, v140
	v_add_u32_e32 v8, 32, v4
	v_bitop3_b32 v141, v7, v5, v9 bitop3:0xde
	v_lshlrev_b32_e32 v5, 8, v8
	v_bitop3_b32 v182, v5, v7, v9 bitop3:0xf6
	v_and_b32_e32 v5, 0xfffff0, v4
	v_lshlrev_b32_e32 v9, 1, v4
	v_and_or_b32 v5, v9, 8, v5
	v_lshrrev_b32_e32 v9, 1, v4
	v_lshrrev_b32_e32 v5, 1, v5
	v_bfe_u32 v10, v140, 2, 1
	v_and_b32_e32 v11, 3, v4
	v_or_b32_e32 v5, v5, v10
	v_and_or_b32 v9, v9, 4, v11
	v_lshlrev_b32_e32 v11, 4, v140
	v_lshlrev_b32_e32 v5, 9, v5
	v_lshlrev_b32_e32 v9, 6, v9
	v_and_b32_e32 v12, 48, v11
	v_or3_b32 v183, v5, v9, v12
	v_and_b32_e32 v5, 0xfffff0, v8
	v_lshlrev_b32_e32 v13, 1, v8
	v_and_or_b32 v5, v13, 8, v5
	v_lshrrev_b32_e32 v5, 1, v5
	v_or_b32_e32 v5, v5, v10
	v_lshlrev_b32_e32 v5, 9, v5
	v_or3_b32 v184, v5, v9, v12
	v_bfe_u32 v12, v140, 2, 6
	v_and_b32_e32 v13, 3, v140
	v_mov_b32_e32 v9, 0x80
	v_lshlrev_b32_e32 v10, 2, v140
	v_lshlrev_b32_e32 v5, 8, v12
	v_lshl_or_b32 v9, v13, 4, v9
	v_and_b32_e32 v10, 0x70, v10
	v_bitop3_b32 v14, v9, v5, v10 bitop3:0xde
	v_lshlrev_b32_e32 v9, 4, v211
	v_lshlrev_b32_e32 v5, 3, v211
	v_and_b32_e32 v9, 0xc0, v9
	v_lshlrev_b32_e32 v10, 1, v211
	v_lshrrev_b32_e32 v1, 5, v211
	v_and_or_b32 v9, v5, 24, v9
	v_and_b32_e32 v10, 32, v10
	v_and_b32_e32 v5, 0x100, v5
	v_and_b32_e32 v0, 31, v140
	v_or3_b32 v15, v9, v10, v5
	v_ashrrev_i32_e32 v5, 31, v4
	v_ashrrev_i32_e32 v9, 31, v8
	v_lshlrev_b32_e32 v187, 4, v1
	v_lshlrev_b64 v[134:135], 12, v[4:5]
	v_lshlrev_b64 v[142:143], 12, v[8:9]
	v_lshlrev_b32_e32 v5, 8, v0
	v_and_b32_e32 v8, 0x70, v11
	v_or_b32_e32 v9, 32, v187
	v_bitop3_b32 v189, v9, v5, v8 bitop3:0xde
	v_or_b32_e32 v9, 64, v187
	v_bitop3_b32 v212, v9, v5, v8 bitop3:0xde
	v_or_b32_e32 v9, 0x60, v187
	s_cmp_lg_u32 0, -1
	v_lshlrev_b32_e32 v4, 3, v13
	v_bitop3_b32 v213, v9, v5, v8 bitop3:0xde
	v_or_b32_e32 v9, 0x80, v187
	s_mov_b64 s[4:5], 0x40000
	s_cselect_b32 s6, 0, 0
	v_lshl_or_b32 v4, v12, 5, v4
	v_bitop3_b32 v214, v9, v5, v8 bitop3:0xde
	v_or_b32_e32 v9, 0xa0, v187
	v_lshl_add_u64 v[144:145], v[134:135], 0, s[4:5]
	s_mov_b64 s[4:5], 0x60000
	s_add_i32 s7, 0, 0xc000
	v_lshlrev_b32_e32 v6, 3, v1
	v_cmp_lt_u32_e64 s[0:1], 7, v3
	s_movk_i32 s2, 0x100
	v_add_u32_e32 v185, s6, v15
	v_lshlrev_b32_e32 v10, 3, v3
	v_bitop3_b32 v188, v187, v5, v8 bitop3:0xde
	v_bitop3_b32 v215, v9, v5, v8 bitop3:0xde
	v_lshl_add_u64 v[146:147], v[134:135], 0, s[4:5]
	s_mov_b64 s[4:5], 0xa0000
	v_mov_b32_e32 v5, s7
	v_cmp_gt_u32_e32 vcc, 8, v3
	s_add_i32 s6, s6, 0x8000
	v_ashrrev_i32_e32 v3, 31, v2
	v_lshlrev_b32_e32 v154, 13, v1
	v_lshlrev_b32_e32 v1, 1, v4
	v_cmp_gt_i32_e64 s[2:3], s2, v140
	v_add_u32_e32 v186, 0, v14
	v_lshl_add_u64 v[148:149], v[134:135], 0, s[56:57]
	v_lshl_add_u64 v[150:151], v[134:135], 0, s[4:5]
	v_cmp_gt_u32_e64 s[4:5], 32, v211
	v_lshl_add_u32 v216, v0, 2, v139
	v_cndmask_b32_e32 v217, 0, v5, vcc
	v_cndmask_b32_e32 v218, v183, v141, vcc
	v_cndmask_b32_e32 v219, v184, v182, vcc
	v_add_u32_e32 v220, s6, v15
	v_lshlrev_b64 v[152:153], 11, v[2:3]
	v_mov_b32_e32 v155, v65
	v_or_b32_e32 v156, v134, v7
	v_mov_b32_e32 v157, v135
	v_or_b32_e32 v158, 0x1d404000, v1
	v_mov_b32_e32 v159, v65
	v_or_b32_e32 v160, 0x1d403000, v1
	v_mov_b32_e32 v161, v65
	v_lshlrev_b32_e32 v64, 1, v6
	v_lshlrev_b32_e32 v162, 1, v10
	v_lshlrev_b32_e32 v164, 1, v4
	v_lshlrev_b32_e32 v166, 1, v0
	v_mov_b32_e32 v232, v139
	v_mov_b32_e32 v233, v187
	v_mov_b32_e32 v234, v216
	v_mov_b32_e32 v235, v185
	v_mov_b32_e32 v236, v188
	v_mov_b32_e32 v237, v189
	v_mov_b32_e32 v238, v212
	v_mov_b32_e32 v239, v213
	v_mov_b32_e32 v242, v186
	v_add_u32_e32 v240, v217, v218
	v_add_u32_e32 v241, v217, v219
	v_lshrrev_b32_e32 v202, 7, v140
	v_lshlrev_b32_e32 v202, 11, v202
	v_bfe_u32 v203, v140, 4, 3
	v_lshl_or_b32 v202, v203, 6, v202
	v_bfe_u32 v203, v140, 2, 1
	v_lshl_or_b32 v202, v203, 9, v202
	v_and_b32_e32 v203, 3, v140
	v_lshl_or_b32 v202, v203, 4, v202
	v_cndmask_b32_e64 v240, v240, v202, s[0:1]
	v_add_u32_e32 v202, 0x2000, v202
	v_cndmask_b32_e64 v241, v241, v202, s[0:1]
	v_lshrrev_b32_e32 v245, 4, v140
	v_and_b32_e32 v246, 15, v140
	v_lshlrev_b32_e32 v243, 12, v245
	v_lshl_or_b32 v243, v246, 4, v243
	v_and_b32_e32 v245, 0xff, v140
	v_lshlrev_b32_e32 v244, 4, v245
	v_readfirstlane_b32 s23, v140
	s_lshr_b32 s23, s23, 6
	s_load_dwordx2 s[26:27], s[94:95], 0xb8
	s_mov_b32 s20, s89
	s_waitcnt lgkmcnt(0)

; __device__ __forceinline__ void qkt(f32x16& p0, f32x16& p1, const char* Ks, const bf16x8* qr, int r32, int hi) {
;     p0 = f32x16{}; p1 = f32x16{};
; #pragma unroll
;     for (int d0 = 0; d0 < 6; ++d0) { const int cb = (d0 * 16 + hi * 8) * 2;
;         bf16x8 b0 = *reinterpret_cast<const bf16x8*>(Ks + KSWZ(r32, cb));
;         bf16x8 b1 = *reinterpret_cast<const bf16x8*>(Ks + KSWZ(32 + r32, cb));
;         p0 = __builtin_amdgcn_mfma_f32_32x32x16_bf16(b0, qr[d0], p0, 0, 0, 0);
;         p1 = __builtin_amdgcn_mfma_f32_32x32x16_bf16(b1, qr[d0], p1, 0, 0, 0); }
; }
.LA_swp:
	v_add_u32_e32 v247, 0x20000, v243
	global_load_dwordx4 v[228:231], v243, s[28:29]
	global_load_dwordx4 v[130:133], v247, s[28:29]
	global_load_dwordx4 v[248:251], v244, s[44:45]
	s_add_u32 s28, s28, 0x40000
	s_addc_u32 s29, s29, 0
	s_add_u32 s44, s44, 0x1000
	s_addc_u32 s45, s45, 0
	v_mov_b32_e32 v141, 0xf149f2ca
	v_mov_b32_e32 v254, 0
	v_mov_b32_e32 v64, 0
	v_mov_b32_e32 v0, 0
	v_mov_b32_e32 v1, 0
	v_mov_b32_e32 v2, 0
	v_mov_b32_e32 v3, 0
	v_mov_b32_e32 v4, 0
	v_mov_b32_e32 v5, 0
	v_mov_b32_e32 v6, 0
	v_mov_b32_e32 v7, 0
	v_mov_b32_e32 v8, 0
	v_mov_b32_e32 v9, 0
	v_mov_b32_e32 v10, 0
	v_mov_b32_e32 v11, 0
	v_mov_b32_e32 v12, 0
	v_mov_b32_e32 v13, 0
	v_mov_b32_e32 v14, 0
	v_mov_b32_e32 v15, 0
	v_mov_b32_e32 v16, 0
	v_mov_b32_e32 v17, 0
	v_mov_b32_e32 v18, 0
	v_mov_b32_e32 v19, 0
	v_mov_b32_e32 v20, 0
	v_mov_b32_e32 v21, 0
	v_mov_b32_e32 v22, 0
	v_mov_b32_e32 v23, 0
	v_mov_b32_e32 v24, 0
	v_mov_b32_e32 v25, 0
	v_mov_b32_e32 v26, 0
	v_mov_b32_e32 v27, 0
	v_mov_b32_e32 v28, 0
	v_mov_b32_e32 v29, 0
	v_mov_b32_e32 v30, 0
	v_mov_b32_e32 v31, 0
	v_mov_b32_e32 v139, 0xf149f2ca
	v_mov_b32_e32 v255, 0
	v_mov_b32_e32 v134, 0
	v_mov_b32_e32 v32, 0
	v_mov_b32_e32 v33, 0
	v_mov_b32_e32 v34, 0
	v_mov_b32_e32 v35, 0
	v_mov_b32_e32 v36, 0
	v_mov_b32_e32 v37, 0
	v_mov_b32_e32 v38, 0
	v_mov_b32_e32 v39, 0
	v_mov_b32_e32 v40, 0
	v_mov_b32_e32 v41, 0
	v_mov_b32_e32 v42, 0
	v_mov_b32_e32 v43, 0
	v_mov_b32_e32 v44, 0
	v_mov_b32_e32 v45, 0
	v_mov_b32_e32 v46, 0
	v_mov_b32_e32 v47, 0
	v_mov_b32_e32 v48, 0
	v_mov_b32_e32 v49, 0
	v_mov_b32_e32 v50, 0
	v_mov_b32_e32 v51, 0
	v_mov_b32_e32 v52, 0
	v_mov_b32_e32 v53, 0
	v_mov_b32_e32 v54, 0
	v_mov_b32_e32 v55, 0
	v_mov_b32_e32 v56, 0
	v_mov_b32_e32 v57, 0
	v_mov_b32_e32 v58, 0
	v_mov_b32_e32 v59, 0
	v_mov_b32_e32 v60, 0
	v_mov_b32_e32 v61, 0
	v_mov_b32_e32 v62, 0
	v_mov_b32_e32 v63, 0
	s_waitcnt lgkmcnt(0)
	s_barrier
.LA_loop:
	v_add_u32_e64 v247, s18, v236
	ds_read_b128 v[212:215], v247 offset:49152
	ds_read_b128 v[216:219], v247 offset:57344
	v_add_u32_e64 v247, s18, v237
	ds_read_b128 v[220:223], v247 offset:49152
	ds_read_b128 v[224:227], v247 offset:57344
	s_waitcnt lgkmcnt(2)
	s_nop 0
	v_mfma_f32_32x32x16_bf16 v[66:81], v[212:215], v[142:145], 0
	v_mfma_f32_32x32x16_bf16 v[82:97], v[216:219], v[142:145], 0
	v_mfma_f32_32x32x16_bf16 v[98:113], v[212:215], v[166:169], 0
	v_mfma_f32_32x32x16_bf16 v[114:129], v[216:219], v[166:169], 0
	v_add_u32_e64 v247, s18, v238
	ds_read_b128 v[212:215], v247 offset:49152
	ds_read_b128 v[216:219], v247 offset:57344
	s_waitcnt lgkmcnt(2)
	s_nop 0
	v_mfma_f32_32x32x16_bf16 v[66:81], v[220:223], v[146:149], v[66:81]
	v_mfma_f32_32x32x16_bf16 v[82:97], v[224:227], v[146:149], v[82:97]
	v_mfma_f32_32x32x16_bf16 v[98:113], v[220:223], v[170:173], v[98:113]
	v_mfma_f32_32x32x16_bf16 v[114:129], v[224:227], v[170:173], v[114:129]
	v_add_u32_e64 v247, s18, v239
	ds_read_b128 v[220:223], v247 offset:49152
	ds_read_b128 v[224:227], v247 offset:57344
	s_waitcnt lgkmcnt(2)
	s_nop 0
	v_mfma_f32_32x32x16_bf16 v[66:81], v[212:215], v[150:153], v[66:81]
	v_mfma_f32_32x32x16_bf16 v[82:97], v[216:219], v[150:153], v[82:97]
	v_mfma_f32_32x32x16_bf16 v[98:113], v[212:215], v[174:177], v[98:113]
	v_mfma_f32_32x32x16_bf16 v[114:129], v[216:219], v[174:177], v[114:129]
	v_add_u32_e64 v247, s18, v236
	ds_read_b128 v[212:215], v247 offset:49280
	ds_read_b128 v[216:219], v247 offset:57472
	s_waitcnt lgkmcnt(2)
	s_nop 0
	v_mfma_f32_32x32x16_bf16 v[66:81], v[220:223], v[154:157], v[66:81]
	v_mfma_f32_32x32x16_bf16 v[82:97], v[224:227], v[154:157], v[82:97]
	v_mfma_f32_32x32x16_bf16 v[98:113], v[220:223], v[178:181], v[98:113]
	v_mfma_f32_32x32x16_bf16 v[114:129], v[224:227], v[178:181], v[114:129]
	v_add_u32_e64 v247, s18, v237
	ds_read_b128 v[220:223], v247 offset:49280
	ds_read_b128 v[224:227], v247 offset:57472
	s_waitcnt lgkmcnt(2)
	s_nop 0
	v_mfma_f32_32x32x16_bf16 v[66:81], v[212:215], v[158:161], v[66:81]
	v_mfma_f32_32x32x16_bf16 v[82:97], v[216:219], v[158:161], v[82:97]
	v_mfma_f32_32x32x16_bf16 v[98:113], v[212:215], v[182:185], v[98:113]
	v_mfma_f32_32x32x16_bf16 v[114:129], v[216:219], v[182:185], v[114:129]
	s_waitcnt lgkmcnt(0)
	s_nop 0
	v_mfma_f32_32x32x16_bf16 v[66:81], v[220:223], v[162:165], v[66:81]
	v_mfma_f32_32x32x16_bf16 v[82:97], v[224:227], v[162:165], v[82:97]
	v_mfma_f32_32x32x16_bf16 v[98:113], v[220:223], v[186:189], v[98:113]
	v_mfma_f32_32x32x16_bf16 v[114:129], v[224:227], v[186:189], v[114:129]
	s_cmp_gt_u32 s16, 62
	s_cbranch_scc1 .LA_nosw
	s_waitcnt vmcnt(0)
	v_add_u32_e32 v246, s19, v240
	v_add_u32_e64 v245, s19, v241
	ds_write_b128 v246, v[228:231]
	ds_write_b128 v245, v[130:133]
	s_cmp_eq_u64 s[2:3], 0
	s_cbranch_scc1 .LA_swl
	v_add_u32_e64 v245, s19, v242
	ds_write_b128 v245, v[248:251] offset:49152

; __device__ __forceinline__ void partialSM(f32x16& p0, f32x16& p1, float& m_reg, float& mn, float& alpha) {
;     constexpr float Cc = SCALE * 1.4426950408889634f;
;     float pmax = p0[0];
; #pragma unroll
;     for (int r = 1; r < 16; ++r) pmax = fmaxf(pmax, p0[r]);
; #pragma unroll
;     for (int r = 0; r < 16; ++r) pmax = fmaxf(pmax, p1[r]);
;     { auto rr = __builtin_amdgcn_permlane32_swap(__float_as_uint(pmax), __float_as_uint(pmax), false, false);
;       pmax = fmaxf(__uint_as_float(rr[0]), __uint_as_float(rr[1])); }
;     if (__builtin_expect(__all(pmax - m_reg <= THR / SCALE), 1)) { mn = m_reg; alpha = 1.f; }
;     else { mn = fmaxf(m_reg, pmax); alpha = __builtin_amdgcn_exp2f((m_reg - mn) * Cc); m_reg = mn; }
;     const float mnC = -mn * Cc;
;     { typedef float f32x2 __attribute__((ext_vector_type(2))); const f32x2 c2 = {Cc, Cc}, m2 = {mnC, mnC};
; #pragma unroll
;       for (int r = 0; r < 16; r += 2) { f32x2 t = {p0[r], p0[r + 1]}; t = __builtin_elementwise_fma(t, c2, m2); p0[r] = t.x; p0[r + 1] = t.y; }
; #pragma unroll
;       for (int r = 0; r < 16; r += 2) { f32x2 t = {p1[r], p1[r + 1]}; t = __builtin_elementwise_fma(t, c2, m2); p1[r] = t.x; p1[r + 1] = t.y; } }
; #pragma unroll
;     for (int r = 0; r < 16; ++r) p0[r] = __builtin_amdgcn_exp2f(p0[r]);
; }
; __device__ __forceinline__ void finishSM(f32x16& p0, f32x16& p1, float alpha, float& l_reg, bf16x8& pa0, bf16x8& pa1, bf16x8& pa2, bf16x8& pa3) {
; #pragma unroll
;     for (int r = 0; r < 16; ++r) p1[r] = __builtin_amdgcn_exp2f(p1[r]);
;     float ps;
;     { typedef float f32x2 __attribute__((ext_vector_type(2))); f32x2 s0 = {p0[0], p0[1]}, s1 = {p1[0], p1[1]};
; #pragma unroll
;       for (int r = 2; r < 16; r += 2) { s0 += (f32x2){p0[r], p0[r + 1]}; s1 += (f32x2){p1[r], p1[r + 1]}; }
;       s0 += s1; ps = s0.x + s0.y; }
;     { auto rr = __builtin_amdgcn_permlane32_swap(__float_as_uint(ps), __float_as_uint(ps), false, false);
;       ps = __uint_as_float(rr[0]) + __uint_as_float(rr[1]); }
;     l_reg = l_reg * alpha + ps;
;     ...
;     PK4(p0, 0, pa0); PK4(p0, 8, pa1); PK4(p1, 0, pa2); PK4(p1, 8, pa3);
.LA_nosw:
	v_add_u32_e32 v202, s18, v235
	v_max_f32_e32 v212, v66, v67
	v_max_f32_e32 v213, v82, v83
	v_max3_f32 v212, v212, v68, v69
	v_max3_f32 v213, v213, v84, v85
	v_max3_f32 v212, v212, v70, v71
	v_max3_f32 v213, v213, v86, v87
	v_max3_f32 v212, v212, v72, v73
	v_max3_f32 v213, v213, v88, v89
	v_max3_f32 v212, v212, v74, v75
	v_max3_f32 v213, v213, v90, v91
	v_max3_f32 v212, v212, v76, v77
	v_max3_f32 v213, v213, v92, v93
	v_max3_f32 v212, v212, v78, v79
	v_max3_f32 v213, v213, v94, v95
	v_max3_f32 v212, v212, v80, v81
	v_max3_f32 v213, v213, v96, v97
	v_max_f32_e32 v212, v212, v213
	v_mov_b32_e32 v213, v212
	s_nop 1
	v_permlane32_swap_b32_e32 v212, v213
	v_max_f32_e32 v212, v212, v213
	v_sub_f32_e32 v214, v212, v141
	v_cmp_ge_f32_e32 vcc, s67, v214
	v_max_f32_e32 v212, v141, v212
	v_sub_f32_e64 v214, v141, v212
	v_mul_f32_e32 v214, 0x3e16c740, v214
	v_exp_f32_e64 v215, v214
	s_cmp_eq_u64 vcc, exec
	s_cselect_b64 s[58:59], -1, 0
	v_cndmask_b32_e64 v141, v212, v141, s[58:59]
	v_cndmask_b32_e64 v215, v215, 1.0, s[58:59]
	v_mul_f32_e32 v216, 0xbe16c740, v141
	v_fma_f32 v66, v66, s52, v216
	v_fma_f32 v67, v67, s52, v216
	v_fma_f32 v68, v68, s52, v216
	v_fma_f32 v69, v69, s52, v216
	v_fma_f32 v70, v70, s52, v216
	v_fma_f32 v71, v71, s52, v216
	v_fma_f32 v72, v72, s52, v216
	v_fma_f32 v73, v73, s52, v216
	v_fma_f32 v74, v74, s52, v216
	v_fma_f32 v75, v75, s52, v216
	v_fma_f32 v76, v76, s52, v216
	v_fma_f32 v77, v77, s52, v216
	v_fma_f32 v78, v78, s52, v216
	v_fma_f32 v79, v79, s52, v216
	v_fma_f32 v80, v80, s52, v216
	v_fma_f32 v81, v81, s52, v216
	v_fma_f32 v82, v82, s52, v216
	v_fma_f32 v83, v83, s52, v216
	v_fma_f32 v84, v84, s52, v216
	v_fma_f32 v85, v85, s52, v216
	v_fma_f32 v86, v86, s52, v216
	v_fma_f32 v87, v87, s52, v216
	v_fma_f32 v88, v88, s52, v216
	v_fma_f32 v89, v89, s52, v216
	v_fma_f32 v90, v90, s52, v216
	v_fma_f32 v91, v91, s52, v216
	v_fma_f32 v92, v92, s52, v216
	v_fma_f32 v93, v93, s52, v216
	v_fma_f32 v94, v94, s52, v216
	v_fma_f32 v95, v95, s52, v216
	v_fma_f32 v96, v96, s52, v216
	v_fma_f32 v97, v97, s52, v216
	v_exp_f32_e32 v66, v66
	v_exp_f32_e32 v67, v67
	v_exp_f32_e32 v68, v68
	v_exp_f32_e32 v69, v69
	v_exp_f32_e32 v70, v70
	v_exp_f32_e32 v71, v71
	v_exp_f32_e32 v72, v72
	v_exp_f32_e32 v73, v73
	v_exp_f32_e32 v74, v74
	v_exp_f32_e32 v75, v75
	v_exp_f32_e32 v76, v76
	v_exp_f32_e32 v77, v77
	v_exp_f32_e32 v78, v78
	v_exp_f32_e32 v79, v79
	v_exp_f32_e32 v80, v80
	v_exp_f32_e32 v81, v81
	v_exp_f32_e32 v82, v82
	v_exp_f32_e32 v83, v83
	v_exp_f32_e32 v84, v84
	v_exp_f32_e32 v85, v85
	v_exp_f32_e32 v86, v86
	v_exp_f32_e32 v87, v87
	v_exp_f32_e32 v88, v88
	v_exp_f32_e32 v89, v89
	v_exp_f32_e32 v90, v90
	v_exp_f32_e32 v91, v91
	v_exp_f32_e32 v92, v92
	v_exp_f32_e32 v93, v93
	v_exp_f32_e32 v94, v94
	v_exp_f32_e32 v95, v95
	v_exp_f32_e32 v96, v96
	v_exp_f32_e32 v97, v97
	v_add_f32_e32 v212, v66, v68
	v_add_f32_e32 v213, v67, v69
	v_add_f32_e32 v212, v70, v212
	v_add_f32_e32 v213, v71, v213
	v_add_f32_e32 v212, v72, v212
	v_add_f32_e32 v213, v73, v213
	v_add_f32_e32 v212, v74, v212
	v_add_f32_e32 v213, v75, v213
	v_add_f32_e32 v212, v76, v212
	v_add_f32_e32 v213, v77, v213
	v_add_f32_e32 v212, v78, v212
	v_add_f32_e32 v213, v79, v213
	v_add_f32_e32 v212, v80, v212
	v_add_f32_e32 v213, v81, v213
	v_add_f32_e32 v212, v82, v212
	v_add_f32_e32 v213, v83, v213
	v_add_f32_e32 v212, v84, v212
	v_add_f32_e32 v213, v85, v213
	v_add_f32_e32 v212, v86, v212
	v_add_f32_e32 v213, v87, v213
	v_add_f32_e32 v212, v88, v212
	v_add_f32_e32 v213, v89, v213
	v_add_f32_e32 v212, v90, v212
	v_add_f32_e32 v213, v91, v213
	v_add_f32_e32 v212, v92, v212
	v_add_f32_e32 v213, v93, v213
	v_add_f32_e32 v212, v94, v212
	v_add_f32_e32 v213, v95, v213
	v_add_f32_e32 v212, v96, v212
	v_add_f32_e32 v213, v97, v213
	v_add_f32_e64 v212, v212, v213
	v_fma_f32 v254, v254, v215, v212
	v_cvt_pk_bf16_f32 v66, v66, v67
	v_cvt_pk_bf16_f32 v67, v68, v69
	v_cvt_pk_bf16_f32 v68, v70, v71
	v_cvt_pk_bf16_f32 v69, v72, v73
	v_cvt_pk_bf16_f32 v70, v74, v75
	v_cvt_pk_bf16_f32 v71, v76, v77
	v_cvt_pk_bf16_f32 v72, v78, v79
	v_cvt_pk_bf16_f32 v73, v80, v81
	v_cvt_pk_bf16_f32 v82, v82, v83
	v_cvt_pk_bf16_f32 v83, v84, v85
	v_cvt_pk_bf16_f32 v84, v86, v87
	v_cvt_pk_bf16_f32 v85, v88, v89
	v_cvt_pk_bf16_f32 v86, v90, v91
	v_cvt_pk_bf16_f32 v87, v92, v93
	v_cvt_pk_bf16_f32 v88, v94, v95
	v_cvt_pk_bf16_f32 v89, v96, v97
	v_cmp_gt_f32_e32 vcc, 1.0, v215
	s_cbranch_vccnz .LA_slow0

; __device__ __forceinline__ void partialSM(f32x16& p0, f32x16& p1, float& m_reg, float& mn, float& alpha) {
;     constexpr float Cc = SCALE * 1.4426950408889634f;
;     float pmax = p0[0];
; #pragma unroll
;     for (int r = 1; r < 16; ++r) pmax = fmaxf(pmax, p0[r]);
; #pragma unroll
;     for (int r = 0; r < 16; ++r) pmax = fmaxf(pmax, p1[r]);
;     { auto rr = __builtin_amdgcn_permlane32_swap(__float_as_uint(pmax), __float_as_uint(pmax), false, false);
;       pmax = fmaxf(__uint_as_float(rr[0]), __uint_as_float(rr[1])); }
;     if (__builtin_expect(__all(pmax - m_reg <= THR / SCALE), 1)) { mn = m_reg; alpha = 1.f; }
;     else { mn = fmaxf(m_reg, pmax); alpha = __builtin_amdgcn_exp2f((m_reg - mn) * Cc); m_reg = mn; }
;     const float mnC = -mn * Cc;
;     { typedef float f32x2 __attribute__((ext_vector_type(2))); const f32x2 c2 = {Cc, Cc}, m2 = {mnC, mnC};
; #pragma unroll
;       for (int r = 0; r < 16; r += 2) { f32x2 t = {p0[r], p0[r + 1]}; t = __builtin_elementwise_fma(t, c2, m2); p0[r] = t.x; p0[r + 1] = t.y; }
; #pragma unroll
;       for (int r = 0; r < 16; r += 2) { f32x2 t = {p1[r], p1[r + 1]}; t = __builtin_elementwise_fma(t, c2, m2); p1[r] = t.x; p1[r + 1] = t.y; } }
; #pragma unroll
;     for (int r = 0; r < 16; ++r) p0[r] = __builtin_amdgcn_exp2f(p0[r]);
; }
; __device__ __forceinline__ void finishSM(f32x16& p0, f32x16& p1, float alpha, float& l_reg, bf16x8& pa0, bf16x8& pa1, bf16x8& pa2, bf16x8& pa3) {
; #pragma unroll
;     for (int r = 0; r < 16; ++r) p1[r] = __builtin_amdgcn_exp2f(p1[r]);
;     float ps;
;     { typedef float f32x2 __attribute__((ext_vector_type(2))); f32x2 s0 = {p0[0], p0[1]}, s1 = {p1[0], p1[1]};
; #pragma unroll
;       for (int r = 2; r < 16; r += 2) { s0 += (f32x2){p0[r], p0[r + 1]}; s1 += (f32x2){p1[r], p1[r + 1]}; }
;       s0 += s1; ps = s0.x + s0.y; }
;     { auto rr = __builtin_amdgcn_permlane32_swap(__float_as_uint(ps), __float_as_uint(ps), false, false);
;       ps = __uint_as_float(rr[0]) + __uint_as_float(rr[1]); }
;     l_reg = l_reg * alpha + ps;
;     ...
;     PK4(p0, 0, pa0); PK4(p0, 8, pa1); PK4(p1, 0, pa2); PK4(p1, 8, pa3);
.LA_g1b:
	ds_read_b64_tr_b16 v[74:75], v202 offset:0
	ds_read_b64_tr_b16 v[76:77], v202 offset:2048
	ds_read_b64_tr_b16 v[78:79], v202 offset:4096
	ds_read_b64_tr_b16 v[80:81], v202 offset:6144
	ds_read_b64_tr_b16 v[90:91], v202 offset:8192
	ds_read_b64_tr_b16 v[92:93], v202 offset:10240
	ds_read_b64_tr_b16 v[94:95], v202 offset:12288
	ds_read_b64_tr_b16 v[96:97], v202 offset:14336
	v_max_f32_e32 v212, v98, v99
	v_max_f32_e32 v213, v114, v115
	v_max3_f32 v212, v212, v100, v101
	v_max3_f32 v213, v213, v116, v117
	v_max3_f32 v212, v212, v102, v103
	v_max3_f32 v213, v213, v118, v119
	v_max3_f32 v212, v212, v104, v105
	v_max3_f32 v213, v213, v120, v121
	v_max3_f32 v212, v212, v106, v107
	v_max3_f32 v213, v213, v122, v123
	v_max3_f32 v212, v212, v108, v109
	v_max3_f32 v213, v213, v124, v125
	v_max3_f32 v212, v212, v110, v111
	v_max3_f32 v213, v213, v126, v127
	v_max3_f32 v212, v212, v112, v113
	v_max3_f32 v213, v213, v128, v129
	v_max_f32_e32 v212, v212, v213
	v_mov_b32_e32 v213, v212
	s_nop 1
	v_permlane32_swap_b32_e32 v212, v213
	v_max_f32_e32 v212, v212, v213
	v_sub_f32_e32 v214, v212, v139
	v_cmp_ge_f32_e32 vcc, s67, v214
	v_max_f32_e32 v212, v139, v212
	v_sub_f32_e64 v214, v139, v212
	v_mul_f32_e32 v214, 0x3e16c740, v214
	v_exp_f32_e64 v215, v214
	s_cmp_eq_u64 vcc, exec
	s_cselect_b64 s[58:59], -1, 0
	v_cndmask_b32_e64 v139, v212, v139, s[58:59]
	v_cndmask_b32_e64 v215, v215, 1.0, s[58:59]
	v_mul_f32_e32 v216, 0xbe16c740, v139
	v_fma_f32 v98, v98, s52, v216
	v_fma_f32 v99, v99, s52, v216
	v_fma_f32 v100, v100, s52, v216
	v_fma_f32 v101, v101, s52, v216
	v_fma_f32 v102, v102, s52, v216
	v_fma_f32 v103, v103, s52, v216
	v_fma_f32 v104, v104, s52, v216
	v_fma_f32 v105, v105, s52, v216
	v_fma_f32 v106, v106, s52, v216
	v_fma_f32 v107, v107, s52, v216
	v_fma_f32 v108, v108, s52, v216
	v_fma_f32 v109, v109, s52, v216
	v_fma_f32 v110, v110, s52, v216
	v_fma_f32 v111, v111, s52, v216
	v_fma_f32 v112, v112, s52, v216
	v_fma_f32 v113, v113, s52, v216
	v_fma_f32 v114, v114, s52, v216
	v_fma_f32 v115, v115, s52, v216
	v_fma_f32 v116, v116, s52, v216
	v_fma_f32 v117, v117, s52, v216
	v_fma_f32 v118, v118, s52, v216
	v_fma_f32 v119, v119, s52, v216
	v_fma_f32 v120, v120, s52, v216
	v_fma_f32 v121, v121, s52, v216
	v_fma_f32 v122, v122, s52, v216
	v_fma_f32 v123, v123, s52, v216
	v_fma_f32 v124, v124, s52, v216
	v_fma_f32 v125, v125, s52, v216
	v_fma_f32 v126, v126, s52, v216
	v_fma_f32 v127, v127, s52, v216
	v_fma_f32 v128, v128, s52, v216
	v_fma_f32 v129, v129, s52, v216
	v_exp_f32_e32 v98, v98
	v_exp_f32_e32 v99, v99
	v_exp_f32_e32 v100, v100
	v_exp_f32_e32 v101, v101
	v_exp_f32_e32 v102, v102
	v_exp_f32_e32 v103, v103
	v_exp_f32_e32 v104, v104
	v_exp_f32_e32 v105, v105
	v_exp_f32_e32 v106, v106
	v_exp_f32_e32 v107, v107
	v_exp_f32_e32 v108, v108
	v_exp_f32_e32 v109, v109
	v_exp_f32_e32 v110, v110
	v_exp_f32_e32 v111, v111
	v_exp_f32_e32 v112, v112
	v_exp_f32_e32 v113, v113
	v_exp_f32_e32 v114, v114
	v_exp_f32_e32 v115, v115
	v_exp_f32_e32 v116, v116
	v_exp_f32_e32 v117, v117
	v_exp_f32_e32 v118, v118
	v_exp_f32_e32 v119, v119
	v_exp_f32_e32 v120, v120
	v_exp_f32_e32 v121, v121
	v_exp_f32_e32 v122, v122
	v_exp_f32_e32 v123, v123
	v_exp_f32_e32 v124, v124
	v_exp_f32_e32 v125, v125
	v_exp_f32_e32 v126, v126
	v_exp_f32_e32 v127, v127
	v_exp_f32_e32 v128, v128
	v_exp_f32_e32 v129, v129
	v_add_f32_e32 v212, v98, v100
	v_add_f32_e32 v213, v99, v101
	v_add_f32_e32 v212, v102, v212
	v_add_f32_e32 v213, v103, v213
	v_add_f32_e32 v212, v104, v212
	v_add_f32_e32 v213, v105, v213
	v_add_f32_e32 v212, v106, v212
	v_add_f32_e32 v213, v107, v213
	v_add_f32_e32 v212, v108, v212
	v_add_f32_e32 v213, v109, v213
	v_add_f32_e32 v212, v110, v212
	v_add_f32_e32 v213, v111, v213
	v_add_f32_e32 v212, v112, v212
	v_add_f32_e32 v213, v113, v213
	v_add_f32_e32 v212, v114, v212
	v_add_f32_e32 v213, v115, v213
	v_add_f32_e32 v212, v116, v212
	v_add_f32_e32 v213, v117, v213
	v_add_f32_e32 v212, v118, v212
	v_add_f32_e32 v213, v119, v213
	v_add_f32_e32 v212, v120, v212
	v_add_f32_e32 v213, v121, v213
	v_add_f32_e32 v212, v122, v212
	v_add_f32_e32 v213, v123, v213
	v_add_f32_e32 v212, v124, v212
	v_add_f32_e32 v213, v125, v213
	v_add_f32_e32 v212, v126, v212
	v_add_f32_e32 v213, v127, v213
	v_add_f32_e32 v212, v128, v212
	v_add_f32_e32 v213, v129, v213
	v_add_f32_e64 v212, v212, v213
	v_fma_f32 v255, v255, v215, v212
	v_cvt_pk_bf16_f32 v98, v98, v99
	v_cvt_pk_bf16_f32 v99, v100, v101
	v_cvt_pk_bf16_f32 v100, v102, v103
	v_cvt_pk_bf16_f32 v101, v104, v105
	v_cvt_pk_bf16_f32 v102, v106, v107
	v_cvt_pk_bf16_f32 v103, v108, v109
	v_cvt_pk_bf16_f32 v104, v110, v111
	v_cvt_pk_bf16_f32 v105, v112, v113
	v_cvt_pk_bf16_f32 v114, v114, v115
	v_cvt_pk_bf16_f32 v115, v116, v117
	v_cvt_pk_bf16_f32 v116, v118, v119
	v_cvt_pk_bf16_f32 v117, v120, v121
	v_cvt_pk_bf16_f32 v118, v122, v123
	v_cvt_pk_bf16_f32 v119, v124, v125
	v_cvt_pk_bf16_f32 v120, v126, v127
	v_cvt_pk_bf16_f32 v121, v128, v129
	v_cmp_gt_f32_e32 vcc, 1.0, v215
	s_cbranch_vccnz .LA_slow1
